# H0 in the P region + XCD-contiguous pooling row-chunk mapping + softmax self-max trim
# speedup vs baseline: 1.0023x; 1.0023x over previous
; #define FRESH() int gtid; do { int t_ = threadIdx.x; asm volatile("" : "+v"(t_)); F.tid = t_; F.lane = t_ & 63; gtid = blockIdx.x * (NWAVES * 64) + t_; (void)gtid; } while (0)
; __global__ void __launch_bounds__(NWAVES * 64, 2) mk_fwd(Args args) {
;     ...
;     if (IN(3)) { FRESH();
;         for (int item = gtid; item < (MT / 8) * 256; item += NTHR) {
;             const int cc = item & 255, row0 = (item >> 8) * 8;
;             int base, L; if (row0 < ML) { base = row0 & ~(SEQ - 1); L = SEQ; } else { base = ML + ((row0 - ML) & ~(CTXL - 1)); L = CTXL; }
;             const int t0 = row0 - base, gidx = cc >> 6;
;             const bf16_t* Ub = U + (size_t)base * DM + cc * 8; bf16_t* Pb = P + (size_t)base * DM + cc * 8;
.LBB0_379:
	s_add_u32 s12, s84, 0x4000000
	s_addc_u32 s13, s85, 0
	s_cmp_lt_i32 s86, 4
	s_cselect_b64 s[0:1], -1, 0
	s_add_u32 s6, s84, 0x1a800000
	s_addc_u32 s7, s85, 0
	s_and_b64 s[4:5], s[0:1], s[4:5]
	s_andn2_b64 vcc, exec, s[4:5]
	s_cbranch_vccnz .LBB0_512
	v_mov_b32_e32 v0, v198
	s_mov_b32 s4, 0x90000
	s_and_b32 s8, s2, 7
	s_lshl_b32 s8, s8, 5
	s_lshr_b32 s9, s2, 3
	s_add_i32 s8, s8, s9
	s_cmpk_eq_i32 s63, 0x100
	s_cselect_b32 s8, s8, s2
	v_lshl_add_u32 v130, s8, 9, v0
	v_cmp_gt_i32_e32 vcc, s4, v130
	s_and_saveexec_b64 s[4:5], vcc
	s_cbranch_execz .LBB0_511
	v_mov_b32_e32 v1, 4
	v_lshlrev_b32_sdwa v92, v1, v0 dst_sel:DWORD dst_unused:UNUSED_PAD src0_sel:DWORD src1_sel:BYTE_0
	v_mov_b32_e32 v93, 0
	v_bfe_u32 v131, v0, 6, 2
	v_lshl_add_u64 v[94:95], s[16:17], 0, v[92:93]
	v_lshl_add_u64 v[96:97], s[6:7], 0, v[92:93]
	s_mov_b64 s[8:9], 0
	s_movk_i32 s22, 0x4000
	v_mov_b32_e32 v132, 0x100
	v_mov_b32_e32 v133, 0x800
	v_mov_b32_e32 v134, 0xffffff00
	v_mov_b32_e32 v135, 0xfffff800
	s_mov_b32 s23, 0x8ffff
	s_branch .LBB0_385
